# P0 weight conversion: hand-written tr_item (16 loads in flight) + tr items rebalanced away from waves that also own a Ua item
# speedup vs baseline: 1.0116x; 1.0116x over previous
; #define LAS __attribute__((address_space(3)))
; #define LDS_WAIT() asm volatile("s_waitcnt lgkmcnt(0)" ::: "memory")
; __device__ __forceinline__ void tr_item(const float* W, int ldn, int col0, int k0, const float* g, bf16* WT, int ldk, int drow0, LAS float* scr, int lane) {
;     const int n4 = (lane & 15) * 4, kr = lane >> 4;
; #pragma unroll
;     for (int i = 0; i < 16; ++i) { const int kk = 4 * i + kr; f32x4 v = *(const f32x4*)(W + (size_t)(k0 + kk) * ldn + col0 + n4); if (g) v = v * g[k0 + kk];
;         LAS float* d = scr + kk * 65 + n4; d[0] = v.x; d[1] = v.y; d[2] = v.z; d[3] = v.w; }
;     LDS_WAIT(); asm volatile("" ::: "memory");
.Ltr_gdone:
	global_load_dwordx4 v[146:149], v232, s[2:3]
	v_add_u32_e32 v232, s38, v232
	global_load_dwordx4 v[150:153], v232, s[2:3]
	v_add_u32_e32 v232, s38, v232
	global_load_dwordx4 v[154:157], v232, s[2:3]
	v_add_u32_e32 v232, s38, v232
	global_load_dwordx4 v[158:161], v232, s[2:3]
	v_add_u32_e32 v232, s38, v232
	global_load_dwordx4 v[162:165], v232, s[2:3]
	v_add_u32_e32 v232, s38, v232
	global_load_dwordx4 v[166:169], v232, s[2:3]
	v_add_u32_e32 v232, s38, v232
	global_load_dwordx4 v[170:173], v232, s[2:3]
	v_add_u32_e32 v232, s38, v232
	global_load_dwordx4 v[174:177], v232, s[2:3]
	v_add_u32_e32 v232, s38, v232
	global_load_dwordx4 v[178:181], v232, s[2:3]
	v_add_u32_e32 v232, s38, v232
	global_load_dwordx4 v[182:185], v232, s[2:3]
	v_add_u32_e32 v232, s38, v232
	global_load_dwordx4 v[186:189], v232, s[2:3]
	v_add_u32_e32 v232, s38, v232
	global_load_dwordx4 v[190:193], v232, s[2:3]
	v_add_u32_e32 v232, s38, v232
	global_load_dwordx4 v[114:117], v232, s[2:3]
	v_add_u32_e32 v232, s38, v232
	global_load_dwordx4 v[118:121], v232, s[2:3]
	v_add_u32_e32 v232, s38, v232
	global_load_dwordx4 v[122:125], v232, s[2:3]
	v_add_u32_e32 v232, s38, v232
	global_load_dwordx4 v[126:129], v232, s[2:3]
	s_waitcnt vmcnt(15)
	v_mul_f32_e32 v146, v210, v146
	v_mul_f32_e32 v147, v210, v147
	v_mul_f32_e32 v148, v210, v148
	v_mul_f32_e32 v149, v210, v149
	ds_write2_b32 v242, v146, v147 offset1:1
	ds_write2_b32 v242, v148, v149 offset0:2 offset1:3
	v_add_u32_e32 v242, 0x410, v242
	s_waitcnt vmcnt(14)
	v_mul_f32_e32 v150, v211, v150
	v_mul_f32_e32 v151, v211, v151
	v_mul_f32_e32 v152, v211, v152
	v_mul_f32_e32 v153, v211, v153
	ds_write2_b32 v242, v150, v151 offset1:1
	ds_write2_b32 v242, v152, v153 offset0:2 offset1:3
	v_add_u32_e32 v242, 0x410, v242
	s_waitcnt vmcnt(13)
	v_mul_f32_e32 v154, v212, v154
	v_mul_f32_e32 v155, v212, v155
	v_mul_f32_e32 v156, v212, v156
	v_mul_f32_e32 v157, v212, v157
	ds_write2_b32 v242, v154, v155 offset1:1
	ds_write2_b32 v242, v156, v157 offset0:2 offset1:3
	v_add_u32_e32 v242, 0x410, v242
	s_waitcnt vmcnt(12)
	v_mul_f32_e32 v158, v213, v158
	v_mul_f32_e32 v159, v213, v159
	v_mul_f32_e32 v160, v213, v160
	v_mul_f32_e32 v161, v213, v161
	ds_write2_b32 v242, v158, v159 offset1:1
	ds_write2_b32 v242, v160, v161 offset0:2 offset1:3
	v_add_u32_e32 v242, 0x410, v242
	s_waitcnt vmcnt(11)
	v_mul_f32_e32 v162, v214, v162
	v_mul_f32_e32 v163, v214, v163
	v_mul_f32_e32 v164, v214, v164
	v_mul_f32_e32 v165, v214, v165
	ds_write2_b32 v242, v162, v163 offset1:1
	ds_write2_b32 v242, v164, v165 offset0:2 offset1:3
	v_add_u32_e32 v242, 0x410, v242
	s_waitcnt vmcnt(10)
	v_mul_f32_e32 v166, v215, v166
	v_mul_f32_e32 v167, v215, v167
	v_mul_f32_e32 v168, v215, v168
	v_mul_f32_e32 v169, v215, v169
	ds_write2_b32 v242, v166, v167 offset1:1
	ds_write2_b32 v242, v168, v169 offset0:2 offset1:3
	v_add_u32_e32 v242, 0x410, v242
	s_waitcnt vmcnt(9)
	v_mul_f32_e32 v170, v216, v170
	v_mul_f32_e32 v171, v216, v171
	v_mul_f32_e32 v172, v216, v172
	v_mul_f32_e32 v173, v216, v173
	ds_write2_b32 v242, v170, v171 offset1:1
	ds_write2_b32 v242, v172, v173 offset0:2 offset1:3
	v_add_u32_e32 v242, 0x410, v242
	s_waitcnt vmcnt(8)
	v_mul_f32_e32 v174, v217, v174
	v_mul_f32_e32 v175, v217, v175
	v_mul_f32_e32 v176, v217, v176
	v_mul_f32_e32 v177, v217, v177
	ds_write2_b32 v242, v174, v175 offset1:1
	ds_write2_b32 v242, v176, v177 offset0:2 offset1:3
	v_add_u32_e32 v242, 0x410, v242
	s_waitcnt vmcnt(7)
	v_mul_f32_e32 v178, v218, v178
	v_mul_f32_e32 v179, v218, v179
	v_mul_f32_e32 v180, v218, v180
	v_mul_f32_e32 v181, v218, v181
	ds_write2_b32 v242, v178, v179 offset1:1
	ds_write2_b32 v242, v180, v181 offset0:2 offset1:3
	v_add_u32_e32 v242, 0x410, v242
	s_waitcnt vmcnt(6)
	v_mul_f32_e32 v182, v219, v182
	v_mul_f32_e32 v183, v219, v183
	v_mul_f32_e32 v184, v219, v184
	v_mul_f32_e32 v185, v219, v185
	ds_write2_b32 v242, v182, v183 offset1:1
	ds_write2_b32 v242, v184, v185 offset0:2 offset1:3
	v_add_u32_e32 v242, 0x410, v242
	s_waitcnt vmcnt(5)
	v_mul_f32_e32 v186, v220, v186
	v_mul_f32_e32 v187, v220, v187
	v_mul_f32_e32 v188, v220, v188
	v_mul_f32_e32 v189, v220, v189
	ds_write2_b32 v242, v186, v187 offset1:1
	ds_write2_b32 v242, v188, v189 offset0:2 offset1:3
	v_add_u32_e32 v242, 0x410, v242
	s_waitcnt vmcnt(4)
	v_mul_f32_e32 v190, v221, v190
	v_mul_f32_e32 v191, v221, v191
	v_mul_f32_e32 v192, v221, v192
	v_mul_f32_e32 v193, v221, v193
	ds_write2_b32 v242, v190, v191 offset1:1
	ds_write2_b32 v242, v192, v193 offset0:2 offset1:3
	v_add_u32_e32 v242, 0x410, v242
	s_waitcnt vmcnt(3)
; #define LAS __attribute__((address_space(3)))
; __device__ __forceinline__ unsigned pk2(float lo, float hi) { return f2bf(lo) | (f2bf(hi) << 16); }
; #define LDS_WAIT() asm volatile("s_waitcnt lgkmcnt(0)" ::: "memory")
; __device__ __forceinline__ void tr_item(const float* W, int ldn, int col0, int k0, const float* g, bf16* WT, int ldk, int drow0, LAS float* scr, int lane) {
;     ...
;     LDS_WAIT(); asm volatile("" ::: "memory");
;     const int c = lane & 7;
; #pragma unroll
;     for (int j = 0; j < 8; ++j) { const int n = (lane >> 3) + 8 * j; const LAS float* s = scr + (8 * c) * 65 + n;
;         v4u o; o.x = pk2(s[0 * 65], s[1 * 65]); o.y = pk2(s[2 * 65], s[3 * 65]); o.z = pk2(s[4 * 65], s[5 * 65]); o.w = pk2(s[6 * 65], s[7 * 65]);
;         *(v4u*)(WT + (size_t)(drow0 + n) * ldk + k0 + 8 * c) = o; }
;     LDS_WAIT(); asm volatile("" ::: "memory");
; __device__ __forceinline__ void phase_prologue(PtrTab TB, unsigned char* ws, float* xout, int l, LAS unsigned char* lds, int gw, int NGW, int lane, int wave) {
;     ...
;     for (int it = gw; it < S14; it += NGW) {
	v_mul_f32_e32 v114, v222, v114
	v_mul_f32_e32 v115, v222, v115
	v_mul_f32_e32 v116, v222, v116
	v_mul_f32_e32 v117, v222, v117
	ds_write2_b32 v242, v114, v115 offset1:1
	ds_write2_b32 v242, v116, v117 offset0:2 offset1:3
	v_add_u32_e32 v242, 0x410, v242
	s_waitcnt vmcnt(2)
	v_mul_f32_e32 v118, v223, v118
	v_mul_f32_e32 v119, v223, v119
	v_mul_f32_e32 v120, v223, v120
	v_mul_f32_e32 v121, v223, v121
	ds_write2_b32 v242, v118, v119 offset1:1
	ds_write2_b32 v242, v120, v121 offset0:2 offset1:3
	v_add_u32_e32 v242, 0x410, v242
	s_waitcnt vmcnt(1)
	v_mul_f32_e32 v122, v230, v122
	v_mul_f32_e32 v123, v230, v123
	v_mul_f32_e32 v124, v230, v124
	v_mul_f32_e32 v125, v230, v125
	ds_write2_b32 v242, v122, v123 offset1:1
	ds_write2_b32 v242, v124, v125 offset0:2 offset1:3
	v_add_u32_e32 v242, 0x410, v242
	s_waitcnt vmcnt(0)
	v_mul_f32_e32 v126, v231, v126
	v_mul_f32_e32 v127, v231, v127
	v_mul_f32_e32 v128, v231, v128
	v_mul_f32_e32 v129, v231, v129
	ds_write2_b32 v242, v126, v127 offset1:1
	ds_write2_b32 v242, v128, v129 offset0:2 offset1:3
	s_waitcnt lgkmcnt(0)
	ds_read2_b32 v[146:147], v62 offset0:0 offset1:65
	ds_read2_b32 v[148:149], v62 offset0:130 offset1:195
	ds_read2_b32 v[150:151], v243 offset0:4 offset1:69
	ds_read2_b32 v[152:153], v243 offset0:134 offset1:199
	ds_read2_b32 v[154:155], v62 offset0:8 offset1:73
	ds_read2_b32 v[156:157], v62 offset0:138 offset1:203
	ds_read2_b32 v[158:159], v243 offset0:12 offset1:77
	ds_read2_b32 v[160:161], v243 offset0:142 offset1:207
	ds_read2_b32 v[162:163], v62 offset0:16 offset1:81
	ds_read2_b32 v[164:165], v62 offset0:146 offset1:211
	ds_read2_b32 v[166:167], v243 offset0:20 offset1:85
	ds_read2_b32 v[168:169], v243 offset0:150 offset1:215
	s_waitcnt lgkmcnt(8)
	v_cvt_pk_bf16_f32 v146, v146, v147
	v_cvt_pk_bf16_f32 v147, v148, v149
	v_cvt_pk_bf16_f32 v148, v150, v151
	v_cvt_pk_bf16_f32 v149, v152, v153
	global_store_dwordx4 v244, v[146:149], s[24:25]
	ds_read2_b32 v[170:171], v62 offset0:24 offset1:89
	ds_read2_b32 v[172:173], v62 offset0:154 offset1:219
	ds_read2_b32 v[174:175], v243 offset0:28 offset1:93
	ds_read2_b32 v[176:177], v243 offset0:158 offset1:223
	s_waitcnt lgkmcnt(8)
	v_cvt_pk_bf16_f32 v154, v154, v155
	v_cvt_pk_bf16_f32 v155, v156, v157
	v_cvt_pk_bf16_f32 v156, v158, v159
	v_cvt_pk_bf16_f32 v157, v160, v161
	global_store_dwordx4 v245, v[154:157], s[24:25]
	ds_read2_b32 v[178:179], v62 offset0:32 offset1:97
	ds_read2_b32 v[180:181], v62 offset0:162 offset1:227
	ds_read2_b32 v[182:183], v243 offset0:36 offset1:101
	ds_read2_b32 v[184:185], v243 offset0:166 offset1:231
	s_waitcnt lgkmcnt(8)
	v_cvt_pk_bf16_f32 v162, v162, v163
	v_cvt_pk_bf16_f32 v163, v164, v165
	v_cvt_pk_bf16_f32 v164, v166, v167
	v_cvt_pk_bf16_f32 v165, v168, v169
	global_store_dwordx4 v246, v[162:165], s[24:25]
	ds_read2_b32 v[186:187], v62 offset0:40 offset1:105
	ds_read2_b32 v[188:189], v62 offset0:170 offset1:235
	ds_read2_b32 v[190:191], v243 offset0:44 offset1:109
	ds_read2_b32 v[192:193], v243 offset0:174 offset1:239
	s_waitcnt lgkmcnt(8)
	v_cvt_pk_bf16_f32 v170, v170, v171
	v_cvt_pk_bf16_f32 v171, v172, v173
	v_cvt_pk_bf16_f32 v172, v174, v175
	v_cvt_pk_bf16_f32 v173, v176, v177
	global_store_dwordx4 v247, v[170:173], s[24:25]
	ds_read2_b32 v[114:115], v62 offset0:48 offset1:113
	ds_read2_b32 v[116:117], v62 offset0:178 offset1:243
	ds_read2_b32 v[118:119], v243 offset0:52 offset1:117
	ds_read2_b32 v[120:121], v243 offset0:182 offset1:247
	s_waitcnt lgkmcnt(8)
	v_cvt_pk_bf16_f32 v178, v178, v179
	v_cvt_pk_bf16_f32 v179, v180, v181
	v_cvt_pk_bf16_f32 v180, v182, v183
	v_cvt_pk_bf16_f32 v181, v184, v185
	global_store_dwordx4 v248, v[178:181], s[24:25]
	ds_read2_b32 v[122:123], v62 offset0:56 offset1:121
	ds_read2_b32 v[124:125], v62 offset0:186 offset1:251
	ds_read2_b32 v[126:127], v243 offset0:60 offset1:125
	ds_read2_b32 v[128:129], v243 offset0:190 offset1:255
	s_waitcnt lgkmcnt(8)
	v_cvt_pk_bf16_f32 v186, v186, v187
	v_cvt_pk_bf16_f32 v187, v188, v189
	v_cvt_pk_bf16_f32 v188, v190, v191
	v_cvt_pk_bf16_f32 v189, v192, v193
	global_store_dwordx4 v249, v[186:189], s[24:25]
	s_waitcnt lgkmcnt(4)
	v_cvt_pk_bf16_f32 v114, v114, v115
	v_cvt_pk_bf16_f32 v115, v116, v117
	v_cvt_pk_bf16_f32 v116, v118, v119
	v_cvt_pk_bf16_f32 v117, v120, v121
	global_store_dwordx4 v250, v[114:117], s[24:25]
	s_waitcnt lgkmcnt(0)
	v_cvt_pk_bf16_f32 v122, v122, v123
	v_cvt_pk_bf16_f32 v123, v124, v125
	v_cvt_pk_bf16_f32 v124, v126, v127
	v_cvt_pk_bf16_f32 v125, v128, v129
	global_store_dwordx4 v251, v[122:125], s[24:25]
	s_cmpk_eq_u32 s8, 0x800
	s_cbranch_scc0 .LBB0_22
	s_cmpk_lt_u32 s10, 0x400
	s_cbranch_scc1 .LBB0_214
	s_addk_i32 s71, 0x400
	s_cmpk_gt_i32 s71, 0x1e3f
	s_cbranch_scc1 .LBB0_214
	s_branch .LBB0_23
